# strategy 7.3: attention epilogues (A non-combine, C, B) store via v_permlane32_swap pairs + dwordx4 instead of dwordx2
# speedup vs baseline: 1.0024x; 1.0024x over previous
; __device__ __forceinline__ unsigned cvtpk(float lo, float hi) { f32x2_t v = {lo, hi}; bf16x2_t b = __builtin_convertvector(v, bf16x2_t); return __builtin_bit_cast(unsigned, b); }
; __device__ __forceinline__ void attn_unit_a(FLAS unsigned char* lds, const Unit u) {
;     ...
; #pragma unroll
;     for (int db = 0; db < NDB; ++db)
; #pragma unroll
;         for (int g = 0; g < 4; ++g) { u32x2 w; w.x = cvtpk(o[db][4 * g] * inv, o[db][4 * g + 1] * inv); w.y = cvtpk(o[db][4 * g + 2] * inv, o[db][4 * g + 3] * inv);
;             *(u32x2*)(op + db * 32 + 8 * g) = w; }
.LBB0_481:
	s_andn2_b64 vcc, exec, s[4:5]
	v_mov_b64_e32 v[232:233], v[218:219]
	s_cbranch_vccnz .LBB0_415
	v_lshl_add_u64 v[72:73], v[64:65], 0, v[208:209]
	v_pk_mul_f32 v[48:49], v[48:49], v[66:67] op_sel_hi:[1,0]
	v_pk_mul_f32 v[50:51], v[50:51], v[66:67] op_sel_hi:[1,0]
	v_pk_mul_f32 v[52:53], v[52:53], v[66:67] op_sel_hi:[1,0]
	v_pk_mul_f32 v[54:55], v[54:55], v[66:67] op_sel_hi:[1,0]
	v_cvt_pk_bf16_f32 v48, v48, v49
	v_cvt_pk_bf16_f32 v49, v50, v51
	v_cvt_pk_bf16_f32 v50, v52, v53
	v_cvt_pk_bf16_f32 v51, v54, v55
	v_pk_mul_f32 v[56:57], v[56:57], v[66:67] op_sel_hi:[1,0]
	v_pk_mul_f32 v[58:59], v[58:59], v[66:67] op_sel_hi:[1,0]
	v_pk_mul_f32 v[60:61], v[60:61], v[66:67] op_sel_hi:[1,0]
	v_pk_mul_f32 v[62:63], v[62:63], v[66:67] op_sel_hi:[1,0]
	v_cvt_pk_bf16_f32 v56, v56, v57
	v_cvt_pk_bf16_f32 v57, v58, v59
	v_cvt_pk_bf16_f32 v58, v60, v61
	v_cvt_pk_bf16_f32 v59, v62, v63
	v_permlane32_swap_b32 v48, v50
	v_permlane32_swap_b32 v49, v51
	global_store_dwordx4 v[72:73], v[48:51], off
	v_pk_mul_f32 v[32:33], v[32:33], v[66:67] op_sel_hi:[1,0]
	v_pk_mul_f32 v[34:35], v[34:35], v[66:67] op_sel_hi:[1,0]
	v_pk_mul_f32 v[36:37], v[36:37], v[66:67] op_sel_hi:[1,0]
	v_pk_mul_f32 v[38:39], v[38:39], v[66:67] op_sel_hi:[1,0]
	v_cvt_pk_bf16_f32 v32, v32, v33
	v_cvt_pk_bf16_f32 v33, v34, v35
	v_cvt_pk_bf16_f32 v34, v36, v37
	v_cvt_pk_bf16_f32 v35, v38, v39
	v_permlane32_swap_b32 v56, v58
	v_permlane32_swap_b32 v57, v59
	global_store_dwordx4 v[72:73], v[56:59], off offset:32
	v_pk_mul_f32 v[40:41], v[40:41], v[66:67] op_sel_hi:[1,0]
	v_pk_mul_f32 v[42:43], v[42:43], v[66:67] op_sel_hi:[1,0]
	v_pk_mul_f32 v[44:45], v[44:45], v[66:67] op_sel_hi:[1,0]
	v_pk_mul_f32 v[46:47], v[46:47], v[66:67] op_sel_hi:[1,0]
	v_cvt_pk_bf16_f32 v40, v40, v41
	v_cvt_pk_bf16_f32 v41, v42, v43
	v_cvt_pk_bf16_f32 v42, v44, v45
	v_cvt_pk_bf16_f32 v43, v46, v47
	v_permlane32_swap_b32 v32, v34
	v_permlane32_swap_b32 v33, v35
	global_store_dwordx4 v[72:73], v[32:35], off offset:64
	v_pk_mul_f32 v[16:17], v[16:17], v[66:67] op_sel_hi:[1,0]
	v_pk_mul_f32 v[18:19], v[18:19], v[66:67] op_sel_hi:[1,0]
	v_pk_mul_f32 v[20:21], v[20:21], v[66:67] op_sel_hi:[1,0]
	v_pk_mul_f32 v[22:23], v[22:23], v[66:67] op_sel_hi:[1,0]
	v_cvt_pk_bf16_f32 v16, v16, v17
	v_cvt_pk_bf16_f32 v17, v18, v19
	v_cvt_pk_bf16_f32 v18, v20, v21
	v_cvt_pk_bf16_f32 v19, v22, v23
	v_permlane32_swap_b32 v40, v42
	v_permlane32_swap_b32 v41, v43
	global_store_dwordx4 v[72:73], v[40:43], off offset:96
	v_pk_mul_f32 v[24:25], v[24:25], v[66:67] op_sel_hi:[1,0]
	v_pk_mul_f32 v[26:27], v[26:27], v[66:67] op_sel_hi:[1,0]
	v_pk_mul_f32 v[28:29], v[28:29], v[66:67] op_sel_hi:[1,0]
	v_pk_mul_f32 v[30:31], v[30:31], v[66:67] op_sel_hi:[1,0]
	v_cvt_pk_bf16_f32 v24, v24, v25
	v_cvt_pk_bf16_f32 v25, v26, v27
	v_cvt_pk_bf16_f32 v26, v28, v29
	v_cvt_pk_bf16_f32 v27, v30, v31
	v_permlane32_swap_b32 v16, v18
	v_permlane32_swap_b32 v17, v19
	global_store_dwordx4 v[72:73], v[16:19], off offset:128
	v_pk_mul_f32 v[0:1], v[0:1], v[66:67] op_sel_hi:[1,0]
	v_pk_mul_f32 v[2:3], v[2:3], v[66:67] op_sel_hi:[1,0]
	v_pk_mul_f32 v[4:5], v[4:5], v[66:67] op_sel_hi:[1,0]
	v_pk_mul_f32 v[6:7], v[6:7], v[66:67] op_sel_hi:[1,0]
	v_cvt_pk_bf16_f32 v0, v0, v1
	v_cvt_pk_bf16_f32 v1, v2, v3
	v_cvt_pk_bf16_f32 v2, v4, v5
	v_cvt_pk_bf16_f32 v3, v6, v7
	v_permlane32_swap_b32 v24, v26
	v_permlane32_swap_b32 v25, v27
	global_store_dwordx4 v[72:73], v[24:27], off offset:160
	v_pk_mul_f32 v[8:9], v[8:9], v[66:67] op_sel_hi:[1,0]
	v_pk_mul_f32 v[10:11], v[10:11], v[66:67] op_sel_hi:[1,0]
	v_pk_mul_f32 v[12:13], v[12:13], v[66:67] op_sel_hi:[1,0]
	v_pk_mul_f32 v[14:15], v[14:15], v[66:67] op_sel_hi:[1,0]
	v_cvt_pk_bf16_f32 v68, v12, v13
	v_mov_b64_e32 v[70:71], v[14:15]
	v_cvt_pk_bf16_f32 v8, v8, v9
	v_cvt_pk_bf16_f32 v9, v10, v11
	v_cvt_pk_bf16_f32 v10, v12, v13
	v_cvt_pk_bf16_f32 v11, v14, v15
	v_permlane32_swap_b32 v0, v2
	v_permlane32_swap_b32 v1, v3
	global_store_dwordx4 v[72:73], v[0:3], off offset:192
	s_nop 0
	v_permlane32_swap_b32 v8, v10
	v_permlane32_swap_b32 v9, v11
	global_store_dwordx4 v[72:73], v[8:11], off offset:224
	s_branch .LBB0_415

; __device__ __forceinline__ unsigned cvtpk(float lo, float hi) { f32x2_t v = {lo, hi}; bf16x2_t b = __builtin_convertvector(v, bf16x2_t); return __builtin_bit_cast(unsigned, b); }
; __device__ __forceinline__ float xhalf_sum(float m) { unsigned a = __builtin_bit_cast(unsigned, m), b = a; xswap(a, b); return __builtin_bit_cast(float, a) + __builtin_bit_cast(float, b); }
; template <int MODE> __device__ __forceinline__ void attn_unit(FLAS unsigned char* lds, const Unit u) {
;     ...
;     const float inv = 1.0f / xhalf_sum(lsum);
;     bf16_t* op = u.O + (size_t)(u.tok0 + q) * u.ldo + 4 * hi;
;     ...
;     for (int db = 0; db < NDB; ++db)
; #pragma unroll
;         for (int g = 0; g < 4; ++g) { u32x2 w; w.x = cvtpk(o[db][4 * g] * inv, o[db][4 * g + 1] * inv); w.y = cvtpk(o[db][4 * g + 2] * inv, o[db][4 * g + 3] * inv);
;             *(u32x2*)(op + db * 32 + 8 * g) = w; }
.LBB0_485:
	v_mov_b32_e32 v32, v137
	s_nop 1
	v_permlane32_swap_b32 v137, v32
	s_nop 1
	v_lshlrev_b32_e32 v208, 4, v134
	v_add_f32_e32 v32, v137, v32
	v_div_scale_f32 v33, s[0:1], v32, v32, 1.0
	v_rcp_f32_e32 v34, v33
	v_div_scale_f32 v35, vcc, 1.0, v32, 1.0
	v_readlane_b32 s0, v254, 39
	v_fma_f32 v36, -v33, v34, 1.0
	v_fmac_f32_e32 v34, v36, v34
	v_mul_f32_e32 v36, v35, v34
	v_fma_f32 v37, -v33, v36, v35
	v_fmac_f32_e32 v36, v37, v34
	v_fma_f32 v33, -v33, v36, v35
	v_div_fmas_f32 v33, v33, v34, v36
	v_div_fixup_f32 v32, v33, v32, 1.0
	v_lshl_add_u64 v[34:35], v[96:97], 0, v[208:209]
	v_pk_mul_f32 v[0:1], v[0:1], v[32:33] op_sel_hi:[1,0]
	v_pk_mul_f32 v[2:3], v[2:3], v[32:33] op_sel_hi:[1,0]
	v_pk_mul_f32 v[4:5], v[4:5], v[32:33] op_sel_hi:[1,0]
	v_pk_mul_f32 v[6:7], v[6:7], v[32:33] op_sel_hi:[1,0]
	v_cvt_pk_bf16_f32 v0, v0, v1
	v_cvt_pk_bf16_f32 v1, v2, v3
	v_cvt_pk_bf16_f32 v2, v4, v5
	v_cvt_pk_bf16_f32 v3, v6, v7
	v_pk_mul_f32 v[8:9], v[8:9], v[32:33] op_sel_hi:[1,0]
	v_pk_mul_f32 v[10:11], v[10:11], v[32:33] op_sel_hi:[1,0]
	v_pk_mul_f32 v[12:13], v[12:13], v[32:33] op_sel_hi:[1,0]
	v_pk_mul_f32 v[14:15], v[14:15], v[32:33] op_sel_hi:[1,0]
	v_cvt_pk_bf16_f32 v8, v8, v9
	v_cvt_pk_bf16_f32 v9, v10, v11
	v_cvt_pk_bf16_f32 v10, v12, v13
	v_cvt_pk_bf16_f32 v11, v14, v15
	v_permlane32_swap_b32 v0, v2
	v_permlane32_swap_b32 v1, v3
	global_store_dwordx4 v[34:35], v[0:3], off
	v_pk_mul_f32 v[16:17], v[16:17], v[32:33] op_sel_hi:[1,0]
	v_pk_mul_f32 v[18:19], v[18:19], v[32:33] op_sel_hi:[1,0]
	v_pk_mul_f32 v[20:21], v[20:21], v[32:33] op_sel_hi:[1,0]
	v_pk_mul_f32 v[22:23], v[22:23], v[32:33] op_sel_hi:[1,0]
	v_cvt_pk_bf16_f32 v16, v16, v17
	v_cvt_pk_bf16_f32 v17, v18, v19
	v_cvt_pk_bf16_f32 v18, v20, v21
	v_cvt_pk_bf16_f32 v19, v22, v23
	v_permlane32_swap_b32 v8, v10
	v_permlane32_swap_b32 v9, v11
	global_store_dwordx4 v[34:35], v[8:11], off offset:32
	v_pk_mul_f32 v[24:25], v[24:25], v[32:33] op_sel_hi:[1,0]
	v_pk_mul_f32 v[26:27], v[26:27], v[32:33] op_sel_hi:[1,0]
	v_pk_mul_f32 v[28:29], v[28:29], v[32:33] op_sel_hi:[1,0]
	v_pk_mul_f32 v[30:31], v[30:31], v[32:33] op_sel_hi:[1,0]
	v_cvt_pk_bf16_f32 v24, v24, v25
	v_cvt_pk_bf16_f32 v25, v26, v27
	v_cvt_pk_bf16_f32 v26, v28, v29
	v_cvt_pk_bf16_f32 v27, v30, v31
	v_permlane32_swap_b32 v16, v18
	v_permlane32_swap_b32 v17, v19
	global_store_dwordx4 v[34:35], v[16:19], off offset:64
	s_nop 0
	v_permlane32_swap_b32 v24, v26
	v_permlane32_swap_b32 v25, v27
	global_store_dwordx4 v[34:35], v[24:27], off offset:96
	s_add_i32 s19, s19, s36
	s_add_i32 s15, s15, s36
	s_add_i32 s14, s14, s0
	s_cmpk_gt_i32 s19, 0x3ff
	s_cbranch_scc1 .LBB0_513

; __device__ __forceinline__ unsigned cvtpk(float lo, float hi) { f32x2_t v = {lo, hi}; bf16x2_t b = __builtin_convertvector(v, bf16x2_t); return __builtin_bit_cast(unsigned, b); }
; __device__ __forceinline__ float xhalf_sum(float m) { unsigned a = __builtin_bit_cast(unsigned, m), b = a; xswap(a, b); return __builtin_bit_cast(float, a) + __builtin_bit_cast(float, b); }
; template <int MODE> __device__ __forceinline__ void attn_unit(FLAS unsigned char* lds, const Unit u) {
;     ...
;     const float inv = 1.0f / xhalf_sum(lsum);
;     bf16_t* op = u.O + (size_t)(u.tok0 + q) * u.ldo + 4 * hi;
;     ...
;     for (int db = 0; db < NDB; ++db)
; #pragma unroll
;         for (int g = 0; g < 4; ++g) { u32x2 w; w.x = cvtpk(o[db][4 * g] * inv, o[db][4 * g + 1] * inv); w.y = cvtpk(o[db][4 * g + 2] * inv, o[db][4 * g + 3] * inv);
;             *(u32x2*)(op + db * 32 + 8 * g) = w; }
.LBB0_515:
	v_mov_b32_e32 v33, v146
	s_nop 1
	v_permlane32_swap_b32 v146, v33
	s_nop 1
	s_add_i32 s19, s19, s36
	v_add_f32_e32 v33, v146, v33
	v_div_scale_f32 v34, s[0:1], v33, v33, 1.0
	v_rcp_f32_e32 v35, v34
	v_div_scale_f32 v36, vcc, 1.0, v33, 1.0
	v_readlane_b32 s0, v254, 39
	v_fma_f32 v37, -v34, v35, 1.0
	v_fmac_f32_e32 v35, v37, v35
	v_mul_f32_e32 v37, v36, v35
	v_fma_f32 v38, -v34, v37, v36
	v_fmac_f32_e32 v37, v38, v35
	v_fma_f32 v34, -v34, v37, v36
	v_div_fmas_f32 v34, v34, v35, v37
	v_div_fixup_f32 v34, v34, v33, 1.0
	v_mov_b32_e32 v33, v209
	v_lshl_add_u64 v[32:33], v[32:33], 2, v[96:97]
	v_pk_mul_f32 v[0:1], v[0:1], v[34:35] op_sel_hi:[1,0]
	v_pk_mul_f32 v[2:3], v[2:3], v[34:35] op_sel_hi:[1,0]
	v_pk_mul_f32 v[4:5], v[4:5], v[34:35] op_sel_hi:[1,0]
	v_pk_mul_f32 v[6:7], v[6:7], v[34:35] op_sel_hi:[1,0]
	v_cvt_pk_bf16_f32 v0, v0, v1
	v_cvt_pk_bf16_f32 v1, v2, v3
	v_cvt_pk_bf16_f32 v2, v4, v5
	v_cvt_pk_bf16_f32 v3, v6, v7
	v_pk_mul_f32 v[8:9], v[8:9], v[34:35] op_sel_hi:[1,0]
	v_pk_mul_f32 v[10:11], v[10:11], v[34:35] op_sel_hi:[1,0]
	v_pk_mul_f32 v[12:13], v[12:13], v[34:35] op_sel_hi:[1,0]
	v_pk_mul_f32 v[14:15], v[14:15], v[34:35] op_sel_hi:[1,0]
	v_cvt_pk_bf16_f32 v8, v8, v9
	v_cvt_pk_bf16_f32 v9, v10, v11
	v_cvt_pk_bf16_f32 v10, v12, v13
	v_cvt_pk_bf16_f32 v11, v14, v15
	v_permlane32_swap_b32 v0, v2
	v_permlane32_swap_b32 v1, v3
	global_store_dwordx4 v[32:33], v[0:3], off
	v_pk_mul_f32 v[16:17], v[16:17], v[34:35] op_sel_hi:[1,0]
	v_pk_mul_f32 v[18:19], v[18:19], v[34:35] op_sel_hi:[1,0]
	v_pk_mul_f32 v[20:21], v[20:21], v[34:35] op_sel_hi:[1,0]
	v_pk_mul_f32 v[22:23], v[22:23], v[34:35] op_sel_hi:[1,0]
	v_cvt_pk_bf16_f32 v16, v16, v17
	v_cvt_pk_bf16_f32 v17, v18, v19
	v_cvt_pk_bf16_f32 v18, v20, v21
	v_cvt_pk_bf16_f32 v19, v22, v23
	v_permlane32_swap_b32 v8, v10
	v_permlane32_swap_b32 v9, v11
	global_store_dwordx4 v[32:33], v[8:11], off offset:32
	v_pk_mul_f32 v[24:25], v[24:25], v[34:35] op_sel_hi:[1,0]
	v_pk_mul_f32 v[26:27], v[26:27], v[34:35] op_sel_hi:[1,0]
	v_pk_mul_f32 v[28:29], v[28:29], v[34:35] op_sel_hi:[1,0]
	v_pk_mul_f32 v[30:31], v[30:31], v[34:35] op_sel_hi:[1,0]
	v_cvt_pk_bf16_f32 v24, v24, v25
	v_cvt_pk_bf16_f32 v25, v26, v27
	v_cvt_pk_bf16_f32 v26, v28, v29
	v_cvt_pk_bf16_f32 v27, v30, v31
	v_permlane32_swap_b32 v16, v18
	v_permlane32_swap_b32 v17, v19
	global_store_dwordx4 v[32:33], v[16:19], off offset:64
	s_nop 0
	v_permlane32_swap_b32 v24, v26
	v_permlane32_swap_b32 v25, v27
	global_store_dwordx4 v[32:33], v[24:27], off offset:96
	s_add_i32 s18, s18, s36
	s_add_i32 s39, s39, s0
	s_cmpk_gt_i32 s19, 0x3ff
	s_cbranch_scc1 .LBB0_545
